# P3: idle workgroups 56..104 stream the scan chunk lines of workgroups 0..48 through the shared XCD L2 (discarded loads) so the serial scans hit L2
# speedup vs baseline: 1.0047x; 1.0011x over previous
; __device__ __forceinline__ int lbid() { int b = blockIdx.x; asm volatile("" : "+s"(b)); return b; }
; DI float ret_lg(int h) { return log1pf(-exp2f(-5.0f - (float)h)); }
; DI void chunk_scans(const Args& a, int tid) {
;     const int gt = lbid() * 512 + tid, NT = lgdim() * 512;
;     for (int n = gt; n < 2 * DFF; n += NT) { const float* p1 = (const float*)(a.ws + WS_W + W_PART1) + n; const float* p2 = (const float*)(a.ws + WS_W + W_PART2) + n; float s1 = 0.f, s2 = 0.f;
;     ...
;         if (idx < 16384) { const int b = idx >> 13, rem = (idx & 8191) * 4, h = rem >> 13;
;             bf16_t* p = (bf16_t*)((unsigned char*)a.out + DO_ST) + (size_t)b * NCH * 32768 + rem; const float* dec = (const float*)(a.ws + WS_SDEC) + b * NCH * 4 + h; f32x4 st = {0.f, 0.f, 0.f, 0.f};
; #pragma unroll 1
;             for (int c0 = 0; c0 < NCH; c0 += 16) { u32x2 t[16]; float d[16];
; #pragma unroll
;                 for (int j = 0; j < 16; ++j) { t[j] = *(const u32x2*)(p + (size_t)(c0 + j) * 32768); d[j] = dec[(c0 + j) * 4]; }
; #pragma unroll
;                 for (int j = 0; j < 16; ++j) { u32x2 w; w.x = pk2(st[0], st[1]); w.y = pk2(st[2], st[3]); *(u32x2*)(p + (size_t)(c0 + j) * 32768) = w; st = st * d[j] + bf4_to_f32(t[j]); } }
;         } else if (idx < 16384 + 8192) { const int i2 = idx - 16384, b = i2 >> 12, rem = (i2 & 4095) * 4, h = rem >> 12; const float cd = __expf(ret_lg(h) * 128.0f);
;             bf16_t* p = (bf16_t*)((unsigned char*)a.out + DO_RS) + (size_t)b * NCH * 16384 + rem; f32x4 st = {0.f, 0.f, 0.f, 0.f};
; #pragma unroll 1
;             for (int c0 = 0; c0 < NCH; c0 += 16) { u32x2 t[16];
; #pragma unroll
;                 for (int j = 0; j < 16; ++j) t[j] = *(const u32x2*)(p + (size_t)(c0 + j) * 16384);
; #pragma unroll
;                 for (int j = 0; j < 16; ++j) { u32x2 w; w.x = pk2(st[0], st[1]); w.y = pk2(st[2], st[3]); *(u32x2*)(p + (size_t)(c0 + j) * 16384) = w; st = st * cd + bf4_to_f32(t[j]); } }
;         } else { const int i3 = idx - 16384 - 8192, b = i3 >> 8, ch = i3 & 255;
;             const float* ls = (const float*)(a.ws + WS_LSUM) + ((size_t)b * NCH * 256 + ch) * 2; float* lc = (float*)(a.ws + WS_LCARRY) + (size_t)b * NCH * 256 + ch; float hv = 0.f;
; #pragma unroll 1
;             for (int c0 = 0; c0 < NCH; c0 += 16) { f32x2 t[16];
; #pragma unroll
;                 for (int j = 0; j < 16; ++j) t[j] = *(const f32x2*)(ls + (c0 + j) * 512);
.LBB0_1233:
	s_or_b64 exec, exec, s[16:17]
	v_readlane_b32 s2, v254, 2
	v_readlane_b32 s3, v254, 3
	s_waitcnt lgkmcnt(0)
	s_barrier
	s_load_dwordx4 s[16:19], s[2:3], 0xf0
	s_mov_b32 s2, s77
	v_mbcnt_lo_u32_b32 v0, -1, 0
	v_mbcnt_hi_u32_b32 v0, -1, v0
	s_nop 0
	v_lshl_or_b32 v0, s2, 6, v0
	s_sub_i32 s24, s87, 56
	s_cmp_lt_u32 s24, 49
	s_cbranch_scc0 .Lmy_sh_done
	s_waitcnt lgkmcnt(0)
	s_lshl_b32 s25, s24, 9
	v_add_u32_e32 v142, s25, v0
	s_cmp_lt_u32 s24, 32
	s_cbranch_scc1 .Lmy_sh_ssd
	s_cmp_lt_u32 s24, 48
	s_cbranch_scc1 .Lmy_sh_ret
	v_subrev_u32_e32 v142, 0x6000, v142
	v_lshrrev_b32_e32 v143, 8, v142
	v_lshlrev_b32_e32 v143, 18, v143
	v_and_b32_e32 v142, 0xff, v142
	v_lshl_add_u32 v143, v142, 3, v143
	s_add_u32 s24, s18, 0x2690000
	s_addc_u32 s25, s19, 0
	s_movk_i32 s26, 0x800
	s_branch .Lmy_sh_go
.Lmy_sh_ret:
	v_subrev_u32_e32 v142, 0x4000, v142
	v_lshrrev_b32_e32 v143, 12, v142
	v_lshlrev_b32_e32 v143, 22, v143
	v_and_b32_e32 v142, 0xfff, v142
	v_lshl_add_u32 v143, v142, 3, v143
	s_add_u32 s24, s16, 0x5000000
	s_addc_u32 s25, s17, 0
	s_mov_b32 s26, 0x8000
	s_branch .Lmy_sh_go
.Lmy_sh_ssd:
	v_lshrrev_b32_e32 v143, 13, v142
	v_lshlrev_b32_e32 v143, 23, v143
	v_and_b32_e32 v142, 0x1fff, v142
	v_lshl_add_u32 v143, v142, 3, v143
	s_add_u32 s24, s16, 0x3000000
	s_addc_u32 s25, s17, 0
	s_mov_b32 s26, 0x10000
.Lmy_sh_go:
	s_mov_b32 s27, 8
.Lmy_sh_loop:
	global_load_dword v144, v143, s[24:25]
	s_add_u32 s24, s24, s26
	s_addc_u32 s25, s25, 0
	global_load_dword v145, v143, s[24:25]
	s_add_u32 s24, s24, s26
	s_addc_u32 s25, s25, 0
	global_load_dword v146, v143, s[24:25]
	s_add_u32 s24, s24, s26
	s_addc_u32 s25, s25, 0
	global_load_dword v147, v143, s[24:25]
	s_add_u32 s24, s24, s26
	s_addc_u32 s25, s25, 0
	global_load_dword v148, v143, s[24:25]
	s_add_u32 s24, s24, s26
	s_addc_u32 s25, s25, 0
	global_load_dword v149, v143, s[24:25]
	s_add_u32 s24, s24, s26
	s_addc_u32 s25, s25, 0
	global_load_dword v150, v143, s[24:25]
	s_add_u32 s24, s24, s26
	s_addc_u32 s25, s25, 0
	global_load_dword v151, v143, s[24:25]
	s_add_u32 s24, s24, s26
	s_addc_u32 s25, s25, 0
	global_load_dword v152, v143, s[24:25]
	s_add_u32 s24, s24, s26
	s_addc_u32 s25, s25, 0
	global_load_dword v153, v143, s[24:25]
	s_add_u32 s24, s24, s26
	s_addc_u32 s25, s25, 0
	global_load_dword v154, v143, s[24:25]
	s_add_u32 s24, s24, s26
	s_addc_u32 s25, s25, 0
	global_load_dword v155, v143, s[24:25]
	s_add_u32 s24, s24, s26
	s_addc_u32 s25, s25, 0
	global_load_dword v156, v143, s[24:25]
	s_add_u32 s24, s24, s26
	s_addc_u32 s25, s25, 0
	global_load_dword v157, v143, s[24:25]
	s_add_u32 s24, s24, s26
	s_addc_u32 s25, s25, 0
	global_load_dword v158, v143, s[24:25]
	s_add_u32 s24, s24, s26
	s_addc_u32 s25, s25, 0
	global_load_dword v159, v143, s[24:25]
	s_add_u32 s24, s24, s26
	s_addc_u32 s25, s25, 0
	s_waitcnt vmcnt(16)
	s_sub_i32 s27, s27, 1
	s_cmp_lg_u32 s27, 0
	s_cbranch_scc1 .Lmy_sh_loop
	s_waitcnt vmcnt(0)
.Lmy_sh_done:
	s_mov_b32 s2, s87
	s_nop 0
	v_readlane_b32 s2, v254, 0
	s_mov_b32 s12, s2
	s_mov_b32 s2, s87
	v_readlane_b32 s3, v254, 1
	s_lshl_b32 s7, s2, 9
	v_add_u32_e32 v2, s7, v0
	s_mov_b32 s3, s12
	s_movk_i32 s12, 0x1600
	s_lshl_b32 s20, s3, 9
	v_cmp_gt_i32_e32 vcc, s12, v2
	s_and_saveexec_b64 s[22:23], vcc
	s_cbranch_execz .LBB0_1236
	v_ashrrev_i32_e32 v3, 31, v2
	s_waitcnt lgkmcnt(0)
	v_lshl_add_u64 v[4:5], v[2:3], 2, s[18:19]
	s_mov_b64 s[12:13], 0x1a00000
	s_ashr_i32 s21, s20, 31
	v_lshl_add_u64 v[4:5], v[4:5], 0, s[12:13]
	s_lshl_b64 s[24:25], s[20:21], 2
	s_mov_b64 s[26:27], 0
	v_mov_b32_e32 v3, v2
